# attention K/V prefetch addressing: 32-bit offsets + SGPR base (saddr) instead of 64-bit per-lane pointer math
# speedup vs baseline: 1.0092x; 1.0092x over previous
; __device__ __forceinline__ KP kp_fresh(KP k) { asm volatile("" : "+s"(k)); return k; }
; __device__ __forceinline__ int tid_fresh(int wid) { return wid * 64 + lane_id(); }
; __device__ __forceinline__ void attn_phase(LAS unsigned char* lds, KP kp, int wid0) {
;     kp = kp_fresh(kp); unsigned char* ws = kp->ws;
;     const bf16* Q = (const bf16*)(ws + WS_Q); const bf16* KV = (const bf16*)(ws + WS_KV); const bf16* KR = (const bf16*)(ws + WS_KR); bf16* O = (bf16*)(ws + WS_O);
;     const int tid = tid_fresh(wid0), lane = tid & 63, wid = tid >> 6, r32 = lane & 31, hi = lane >> 5;
;     const int key_l = tid >> 3, c8 = tid & 7;
;     const int kp2 = tid >> 4, g4 = tid & 15;
;     (void)lane;
;     for (int bh = blockIdx.x; bh < NB * NHD; bh += gridDim.x) {
;         const int b = bh >> 4, h = bh & 15, rowb = b * LL;
;         bf16x8 qr[6];
;         u32x4 kregA, rregA = {}, kregB, rregB = {}; u32x2 vaA, vbA, vaB, vbB;
.LBB0_408:
	s_or_b64 exec, exec, s[2:3]
	v_readlane_b32 s0, v255, 3
	v_readlane_b32 s1, v255, 4
	s_mov_b64 s[2:3], s[88:89]
	s_andn2_b64 vcc, exec, s[0:1]
	s_waitcnt lgkmcnt(0)
	s_barrier
	v_mbcnt_lo_u32_b32 v1, -1, 0
	v_mbcnt_hi_u32_b32 v1, -1, v1
	s_cbranch_vccnz .LBB0_477
	s_load_dwordx2 s[0:1], s[2:3], 0x98
	v_add_u32_e32 v2, s61, v1
	v_ashrrev_i32_e32 v11, 6, v2
	v_lshlrev_b32_e32 v12, 5, v11
	v_lshlrev_b32_e32 v4, 4, v1
	v_and_b32_e32 v165, 31, v1
	s_waitcnt lgkmcnt(0)
	s_add_u32 s100, s0, 0xabb0000
	s_addc_u32 s101, s1, 0
	s_add_u32 s48, s0, 0xadb4000
	v_add_u32_e32 v195, 0xffffff10, v12
	v_and_b32_e32 v4, 48, v4
	v_mov_b32_e32 v239, v4
	v_mov_b32_e32 v5, v0
	v_ashrrev_i32_e32 v194, 3, v2
	v_ashrrev_i32_e32 v3, 4, v2
	s_addc_u32 s49, s1, 0
	v_and_b32_e32 v7, 7, v1
	v_add_u32_e32 v2, v195, v165
	v_lshl_add_u64 v[4:5], s[0:1], 0, v[4:5]
	s_mov_b64 s[2:3], 0xabb0000
	s_add_u32 s60, s0, 0x10e74000
	v_max_i32_e32 v196, 0, v2
	v_lshlrev_b32_e32 v2, 3, v7
	v_lshl_add_u64 v[166:167], v[4:5], 0, s[2:3]
	v_lshlrev_b32_e32 v6, 4, v7
	v_mov_b32_e32 v238, v6
	v_cmp_gt_u32_e64 s[2:3], 4, v7
	v_mov_b32_e32 v7, v0
	s_addc_u32 s61, s1, 0
	s_movk_i32 s5, 0xd0
	v_lshl_add_u64 v[8:9], s[0:1], 0, v[6:7]
	s_mov_b64 s[0:1], 0x5300000
	v_lshl_add_u64 v[168:169], v[8:9], 0, s[0:1]
	v_mad_u32_u24 v198, v165, s5, 0
	s_movk_i32 s1, 0xffb8
	v_mad_i32_i24 v200, v165, s1, v198
	s_movk_i32 s0, 0x48
	v_lshl_add_u64 v[170:171], s[60:61], 0, v[6:7]
	v_mad_u32_u24 v202, v165, s0, v200
	v_or_b32_e32 v7, v165, v12
	s_movk_i32 s0, 0x1200
	v_lshlrev_b32_e32 v4, 2, v1
	v_add_u32_e32 v204, 16, v7
	v_mul_lo_u32 v7, v11, s0
	v_bfe_u32 v10, v1, 5, 1
	v_and_b32_e32 v4, 60, v4
	v_mul_lo_u32 v5, v194, s5
	s_movk_i32 s4, 0x88
	v_add_u32_e32 v7, 0, v7
	s_movk_i32 s0, 0x90
	v_bfe_u32 v205, v1, 3, 3
	v_lshlrev_b32_e32 v164, 3, v10
	v_lshlrev_b32_e32 v197, 1, v3
	v_add_u32_e32 v5, 0, v5
	v_mad_u32_u24 v13, v4, s4, 0
	v_lshlrev_b32_e32 v3, 2, v3
	v_mad_u32_u24 v8, v165, s0, v7
	v_add_u32_e32 v1, v7, v6
	v_mul_u32_u24_e32 v7, 0x90, v205
	v_lshlrev_b32_e32 v199, 4, v10
	v_lshlrev_b32_e32 v201, 2, v10
	v_mad_i32_i24 v203, v165, s1, v202
	v_or_b32_e32 v206, 8, v205
	v_or_b32_e32 v207, 16, v205
	v_or_b32_e32 v208, 24, v205
	v_lshlrev_b32_e32 v172, 1, v2
	v_lshlrev_b32_e32 v174, 1, v4
	v_add_u32_e32 v209, v8, v164
	v_add_u32_e32 v210, v5, v6
	v_add_u32_e32 v211, v13, v3
	v_add_u32_e32 v212, v1, v7
	s_mov_b32 s0, s33
	s_branch .LBB0_411

; #define ATT_BAR() do { asm volatile("s_waitcnt lgkmcnt(0)" ::: "memory"); __builtin_amdgcn_s_barrier(); asm volatile("" ::: "memory"); } while (0)
; #define ATT_LOADK(kt_, S_) do { int grow_ = rowb + 64 * (kt_) + key_l; grow_ = grow_ < RR ? grow_ : RR - 1; \
;             kreg##S_ = *(const u32x4*)(KV + (size_t)grow_ * 2048 + h * 128 + c8 * 8); rreg##S_ = *(const u32x4*)(KR + (size_t)grow_ * 32 + (c8 & 3) * 8); } while (0)
; #define ATT_LOADV(kt_, S_) do { int g0_ = rowb + 64 * (kt_) + 2 * kp2, g1_ = g0_ + 1; g0_ = g0_ < RR ? g0_ : RR - 1; g1_ = g1_ < RR ? g1_ : RR - 1; \
;             va##S_ = *(const u32x2*)(KV + (size_t)g0_ * 2048 + h * 128 + 64 + g4 * 4); vb##S_ = *(const u32x2*)(KV + (size_t)g1_ * 2048 + h * 128 + 64 + g4 * 4); } while (0)
; #define ATT_STOREK(slot_, S_) do { LAS unsigned char* kb_ = lds + (slot_) * KBYTES; \
;             *(LAS u32x4*)(kb_ + key_l * KPT + c8 * 16) = kreg##S_; if (c8 < 4) *(LAS u32x4*)(kb_ + key_l * KPT + 128 + c8 * 16) = rreg##S_; } while (0)
; __device__ __forceinline__ void attn_phase(LAS unsigned char* lds, KP kp, int wid0) {
;     ...
;             ATT_STOREK(0, A); ATT_STOREV(0, A);
;             ATT_LOADK(0, A); ATT_LOADV(0, A);
;             ATT_BAR();
;         }
;         for (int j = 0; j < 9; ++j) {
;             const int q0 = j == 0 ? -240 : 16 + 256 * (j - 1);
;             const int NT = (q0 + 256 + 63) >> 6;
;             const int qw0 = q0 + 32 * wid, q = qw0 + r32, qm = q < 0 ? 0 : q;
;             const int qwmax = (qw0 + 31) < 0 ? 0 : (qw0 + 31), qwmin = qw0 < 0 ? 0 : qw0;
;             float m_run = 0.f, l_run = 0.f;
;             f32x16 o0 = {}, o1 = {}, negm = {};
.LBB0_413:
	s_or_b64 exec, exec, s[6:7]
	s_waitcnt vmcnt(1)
	v_and_b32_e32 v1, 0xffff, v188
	v_lshrrev_b32_e32 v2, 16, v188
	s_waitcnt vmcnt(0)
	v_lshl_or_b32 v1, v190, 16, v1
	v_and_or_b32 v2, v190, s81, v2
	v_add_u32_e32 v214, 0x6800, v211
	ds_write2_b32 v214, v1, v2 offset1:34
	v_and_b32_e32 v1, 0xffff, v189
	v_lshrrev_b32_e32 v2, 16, v189
	v_lshl_or_b32 v1, v191, 16, v1
	v_and_or_b32 v2, v191, s81, v2
	s_lshl_b32 s6, s8, 5
	ds_write2_b32 v214, v1, v2 offset0:68 offset1:102
	s_lshl_b32 s4, s4, 1
	s_mov_b32 s5, s87
	s_waitcnt lgkmcnt(0)
	s_barrier
	v_lshl_add_u64 v[178:179], v[170:171], 0, s[4:5]
	s_add_u32 s4, s60, s4
	v_mov_b32_e32 v2, v0
	v_mov_b32_e32 v3, v0
	s_addc_u32 s5, s61, 0
	s_lshl_b32 s86, s86, 1
	v_mov_b32_e32 v1, v0
	v_mov_b64_e32 v[126:127], v[2:3]
	v_add_u32_e32 v215, s1, v204
	v_lshl_add_u64 v[180:181], v[168:169], 0, s[86:87]
	v_or_b32_e32 v216, s1, v205
	v_or_b32_e32 v217, s1, v206
	v_lshl_add_u64 v[182:183], s[4:5], 0, v[174:175]
	s_mov_b64 s[98:99], s[4:5]
	s_mov_b32 s43, 0
	s_lshl_b32 s78, s6, 1
	v_mov_b64_e32 v[124:125], v[0:1]

; #define LAS __attribute__((address_space(3)))
; __device__ __forceinline__ void qk_tile(f32x16& s0, f32x16& s1, LAS unsigned char* kb, const bf16x8 (&qr)[6], const f32x16& negm, int r32, int hi) {
;     bf16x8 kf[12];
; #pragma unroll
;     for (int ks = 0; ks < 6; ++ks) { kf[2 * ks] = *(const LAS bf16x8*)(kb + r32 * KPT + ks * 32 + hi * 16); kf[2 * ks + 1] = *(const LAS bf16x8*)(kb + (32 + r32) * KPT + ks * 32 + hi * 16); }
;     __builtin_amdgcn_sched_barrier(0);
; #pragma unroll
;     for (int ks = 0; ks < 6; ++ks) {
;         s0 = __builtin_amdgcn_mfma_f32_32x32x16_bf16(kf[2 * ks], qr[ks], ks == 0 ? negm : s0, 0, 0, 0);
;         s1 = __builtin_amdgcn_mfma_f32_32x32x16_bf16(kf[2 * ks + 1], qr[ks], ks == 0 ? negm : s1, 0, 0, 0);
;     }
; }
; __device__ __forceinline__ void sm_pv(f32x16& s0, f32x16& s1, f32x16& o0, f32x16& o1, float& m_run, float& l_run, f32x16& negm, LAS unsigned char* vb, bool domask, int kbase, int qm, int r32, int hi) {
;     s16x4 vlo[8], vhh[8];
; #pragma unroll
;     for (int kk = 0; kk < 4; ++kk) { const int koff = 2 * (16 * kk + 4 * hi);
;         vlo[2 * kk] = *(const LAS s16x4*)(vb + r32 * VP + koff); vhh[2 * kk] = *(const LAS s16x4*)(vb + r32 * VP + koff + 16);
;         vlo[2 * kk + 1] = *(const LAS s16x4*)(vb + (32 + r32) * VP + koff); vhh[2 * kk + 1] = *(const LAS s16x4*)(vb + (32 + r32) * VP + koff + 16); }
;     __builtin_amdgcn_sched_barrier(0);
;     if (domask) {
;         const int kb0 = kbase + 4 * hi;
; #pragma unroll
;         for (int r = 0; r < 16; ++r) { const int kv = kb0 + (r & 3) + 8 * (r >> 2); if (kv > qm) s0[r] = -INFINITY; if (kv + 32 > qm) s1[r] = -INFINITY; }
.LBB0_418:
	s_add_i32 s85, s84, -3
	s_cmp_lt_u32 s85, s57
	s_cselect_b64 s[44:45], -1, 0
	s_and_b64 s[4:5], s[44:45], exec
	s_cselect_b32 s4, 0, s79
	s_lshl_b32 s4, s4, 6
	v_add_u32_e32 v221, s83, v213
	v_add_u32_e32 v222, s83, v173
	s_sub_i32 s5, 0x80, s4
	s_waitcnt vmcnt(3)
	v_add_u32_e32 v2, s5, v221
	v_add_u32_e32 v10, s5, v222
	v_min_u32_e32 v2, 0x80ff, v2
	v_add_u32_e32 v12, 1, v10
	v_min_u32_e32 v10, 0x80ff, v10
	v_min_u32_e32 v12, 0x80ff, v12
	v_lshl_add_u32 v4, v2, 12, v238
	s_waitcnt vmcnt(2)
	v_lshl_add_u32 v6, v2, 6, v239
	v_lshl_add_u32 v10, v10, 12, v174
	v_lshl_add_u32 v12, v12, 12, v174
	global_load_dwordx4 v[2:5], v4, s[98:99]
	s_nop 0
	global_load_dwordx4 v[6:9], v6, s[100:101]
	global_load_dwordx2 v[14:15], v10, s[98:99] offset:128
	global_load_dwordx2 v[192:193], v12, s[98:99] offset:128
	v_cmp_le_u32_e32 vcc, s83, v220
	s_and_saveexec_b64 s[46:47], vcc
	s_cbranch_execz .LBB0_426
	v_add_u32_e32 v64, v198, v199
	ds_read_b128 v[10:13], v64 offset:13312
	ds_read_b128 v[136:139], v64 offset:13344
	ds_read_b128 v[140:143], v64 offset:19968
	ds_read_b128 v[144:147], v64 offset:20000
	ds_read_b128 v[148:151], v64 offset:13376
	ds_read_b128 v[152:155], v64 offset:13408
	ds_read_b128 v[156:159], v64 offset:20032
	ds_read_b128 v[160:163], v64 offset:20064
	ds_read_b128 v[224:227], v64 offset:13440
	ds_read_b128 v[228:231], v64 offset:13472
	ds_read_b128 v[232:235], v64 offset:20096
	ds_read_b128 v[246:249], v64 offset:20128
	s_waitcnt lgkmcnt(11)
	v_mfma_f32_32x32x16_bf16 v[80:95], v[10:13], v[96:99], v[48:63]
	v_add_u32_e32 v10, v200, v164
	v_add_u32_e32 v11, 0x8800, v10
	v_add_u32_e32 v10, 0x9800, v10
	s_add_i32 s4, s83, 63
	v_cmp_gt_i32_e32 vcc, s4, v175
	s_waitcnt lgkmcnt(9)
	v_mfma_f32_32x32x16_bf16 v[64:79], v[140:143], v[96:99], v[48:63]
	v_mfma_f32_32x32x16_bf16 v[80:95], v[136:139], v[100:103], v[80:95]
	s_waitcnt lgkmcnt(8)
	v_mfma_f32_32x32x16_bf16 v[64:79], v[144:147], v[100:103], v[64:79]
	s_waitcnt lgkmcnt(7)
	v_mfma_f32_32x32x16_bf16 v[80:95], v[148:151], v[104:107], v[80:95]
	s_waitcnt lgkmcnt(5)
	v_mfma_f32_32x32x16_bf16 v[64:79], v[156:159], v[104:107], v[64:79]
	v_mfma_f32_32x32x16_bf16 v[80:95], v[152:155], v[108:111], v[80:95]
	ds_read2_b64 v[152:155], v11 offset0:68 offset1:70
	s_waitcnt lgkmcnt(5)
	v_mfma_f32_32x32x16_bf16 v[64:79], v[160:163], v[108:111], v[64:79]
	ds_read2_b64 v[160:163], v11 offset0:64 offset1:66
	ds_read2_b64 v[156:159], v10 offset0:96 offset1:98
	ds_read2_b64 v[148:151], v10 offset0:100 offset1:102
	ds_read2_b64 v[144:147], v11 offset0:72 offset1:74
	ds_read2_b64 v[140:143], v10 offset0:104 offset1:106
	ds_read2_b64 v[136:139], v11 offset0:76 offset1:78
	ds_read2_b64 v[10:13], v10 offset0:108 offset1:110
	s_waitcnt lgkmcnt(11)
	v_mfma_f32_32x32x16_bf16 v[80:95], v[224:227], v[112:115], v[80:95]
	s_waitcnt lgkmcnt(9)
	v_mfma_f32_32x32x16_bf16 v[64:79], v[232:235], v[112:115], v[64:79]
	v_mfma_f32_32x32x16_bf16 v[80:95], v[228:231], v[116:119], v[80:95]
	s_waitcnt lgkmcnt(8)
	v_mfma_f32_32x32x16_bf16 v[64:79], v[246:249], v[116:119], v[64:79]
	s_and_saveexec_b64 s[58:59], vcc
	s_cbranch_execz .LBB0_423
	v_add_u32_e32 v223, s83, v201
	v_add_u32_e32 v224, 32, v223
	v_cmp_ge_i32_e64 s[4:5], v177, v224
	v_add_u32_e32 v224, 33, v223
	v_cmp_ge_i32_e64 s[6:7], v177, v224
	v_add_u32_e32 v224, 2, v223
	v_cmp_le_u32_e32 vcc, v223, v219
	s_nop 2
	v_cndmask_b32_e64 v65, v244, v65, s[6:7]
	v_cmp_ge_i32_e64 s[6:7], v177, v224
	v_add_u32_e32 v224, 34, v223
	v_cmp_ge_i32_e64 s[8:9], v177, v224
	v_add_u32_e32 v224, 3, v223
	v_cndmask_b32_e64 v64, v244, v64, s[4:5]
	v_cndmask_b32_e64 v66, v244, v66, s[8:9]
	v_cmp_ge_i32_e64 s[8:9], v177, v224
	v_add_u32_e32 v224, 35, v223
	v_cmp_ge_i32_e64 s[10:11], v177, v224
	v_add_u32_e32 v224, 8, v223
	v_cmp_gt_i32_e64 s[4:5], v177, v223
	v_cndmask_b32_e64 v67, v244, v67, s[10:11]
	v_cmp_ge_i32_e64 s[10:11], v177, v224
	v_add_u32_e32 v224, 40, v223
	v_cmp_ge_i32_e64 s[12:13], v177, v224
	v_add_u32_e32 v224, 9, v223
	s_nop 0
	v_cndmask_b32_e64 v68, v244, v68, s[12:13]
	v_cmp_ge_i32_e64 s[12:13], v177, v224
	v_add_u32_e32 v224, 41, v223
	v_cmp_ge_i32_e64 s[14:15], v177, v224
	v_add_u32_e32 v224, 10, v223
	s_nop 0
	v_cndmask_b32_e64 v69, v244, v69, s[14:15]
	v_cmp_ge_i32_e64 s[14:15], v177, v224
	v_add_u32_e32 v224, 42, v223
	v_cmp_ge_i32_e64 s[16:17], v177, v224
	v_add_u32_e32 v224, 11, v223
	s_nop 0
	v_cndmask_b32_e64 v70, v244, v70, s[16:17]
	v_cmp_ge_i32_e64 s[16:17], v177, v224
	v_add_u32_e32 v224, 43, v223
	v_cmp_ge_i32_e64 s[18:19], v177, v224
	v_add_u32_e32 v224, 16, v223
	s_nop 0
	v_cndmask_b32_e64 v71, v244, v71, s[18:19]
	v_cmp_ge_i32_e64 s[18:19], v177, v224
	v_add_u32_e32 v224, 48, v223
	v_cmp_ge_i32_e64 s[20:21], v177, v224
	v_add_u32_e32 v224, 17, v223
	s_nop 0
	v_cndmask_b32_e64 v72, v244, v72, s[20:21]
	v_cmp_ge_i32_e64 s[20:21], v177, v224
	v_add_u32_e32 v224, 49, v223
	v_cmp_ge_i32_e64 s[22:23], v177, v224
	v_add_u32_e32 v224, 18, v223
	s_nop 0
	v_cndmask_b32_e64 v73, v244, v73, s[22:23]
	v_cmp_ge_i32_e64 s[22:23], v177, v224
	v_add_u32_e32 v224, 50, v223
	v_cmp_ge_i32_e64 s[24:25], v177, v224
	v_add_u32_e32 v224, 19, v223
	s_nop 0
	v_cndmask_b32_e64 v74, v244, v74, s[24:25]
	v_cmp_ge_i32_e64 s[24:25], v177, v224
	v_add_u32_e32 v224, 51, v223
	v_cmp_ge_i32_e64 s[26:27], v177, v224
	v_add_u32_e32 v224, 24, v223
	s_nop 0
	v_cndmask_b32_e64 v75, v244, v75, s[26:27]
	v_cmp_ge_i32_e64 s[26:27], v177, v224
	v_add_u32_e32 v224, 56, v223
	v_cmp_ge_i32_e64 s[28:29], v177, v224
	v_add_u32_e32 v224, 25, v223
	s_nop 0
	v_cndmask_b32_e64 v76, v244, v76, s[28:29]
	v_cmp_ge_i32_e64 s[28:29], v177, v224
	v_add_u32_e32 v224, 57, v223
	v_cmp_ge_i32_e64 s[30:31], v177, v224
	v_add_u32_e32 v224, 26, v223
	s_nop 0
	v_cndmask_b32_e64 v77, v244, v77, s[30:31]
	v_cmp_ge_i32_e64 s[30:31], v177, v224
	v_add_u32_e32 v224, 58, v223
	v_cmp_ge_i32_e64 s[34:35], v177, v224
	v_add_u32_e32 v224, 27, v223
	v_add_u32_e32 v223, 59, v223
	v_cndmask_b32_e64 v78, v244, v78, s[34:35]
	v_cmp_ge_i32_e64 s[34:35], v177, v224
	v_cmp_lt_i32_e64 s[36:37], v177, v223
	s_and_saveexec_b64 s[40:41], s[36:37]
	v_mov_b32_e32 v79, s52
	s_or_b64 exec, exec, s[40:41]
	v_cndmask_b32_e32 v80, v244, v80, vcc
	v_cndmask_b32_e64 v81, v244, v81, s[4:5]
	v_cndmask_b32_e64 v82, v244, v82, s[6:7]
	v_cndmask_b32_e64 v83, v244, v83, s[8:9]
	v_cndmask_b32_e64 v84, v244, v84, s[10:11]
	v_cndmask_b32_e64 v85, v244, v85, s[12:13]
	v_cndmask_b32_e64 v86, v244, v86, s[14:15]
	v_cndmask_b32_e64 v87, v244, v87, s[16:17]
	v_cndmask_b32_e64 v88, v244, v88, s[18:19]
	v_cndmask_b32_e64 v89, v244, v89, s[20:21]
	v_cndmask_b32_e64 v90, v244, v90, s[22:23]
	v_cndmask_b32_e64 v91, v244, v91, s[24:25]
	v_cndmask_b32_e64 v92, v244, v92, s[26:27]
	v_cndmask_b32_e64 v93, v244, v93, s[28:29]
	v_cndmask_b32_e64 v94, v244, v94, s[30:31]
	v_cndmask_b32_e64 v95, v244, v95, s[34:35]

; #define LAS __attribute__((address_space(3)))
; __device__ __forceinline__ void qk_tile(f32x16& s0, f32x16& s1, LAS unsigned char* kb, const bf16x8 (&qr)[6], const f32x16& negm, int r32, int hi) {
;     bf16x8 kf[12];
; #pragma unroll
;     for (int ks = 0; ks < 6; ++ks) { kf[2 * ks] = *(const LAS bf16x8*)(kb + r32 * KPT + ks * 32 + hi * 16); kf[2 * ks + 1] = *(const LAS bf16x8*)(kb + (32 + r32) * KPT + ks * 32 + hi * 16); }
;     __builtin_amdgcn_sched_barrier(0);
; #pragma unroll
;     for (int ks = 0; ks < 6; ++ks) {
;         s0 = __builtin_amdgcn_mfma_f32_32x32x16_bf16(kf[2 * ks], qr[ks], ks == 0 ? negm : s0, 0, 0, 0);
;         s1 = __builtin_amdgcn_mfma_f32_32x32x16_bf16(kf[2 * ks + 1], qr[ks], ks == 0 ? negm : s1, 0, 0, 0);
;     }
.LBB0_426:
	s_or_b64 exec, exec, s[46:47]
	ds_write_b128 v210, v[120:123]
	s_and_saveexec_b64 s[4:5], s[2:3]
	ds_write_b128 v210, v[124:127] offset:128
	s_or_b64 exec, exec, s[4:5]
	s_waitcnt vmcnt(5)
	v_and_b32_e32 v10, 0xffff, v184
	v_lshrrev_b32_e32 v11, 16, v184
	s_waitcnt vmcnt(4)
	v_lshl_or_b32 v10, v186, 16, v10
	v_and_or_b32 v11, v186, s81, v11
	ds_write2_b32 v214, v10, v11 offset1:34
	v_and_b32_e32 v10, 0xffff, v185
	v_lshrrev_b32_e32 v11, 16, v185
	v_lshl_or_b32 v10, v187, 16, v10
	v_and_or_b32 v11, v187, s81, v11
	ds_write2_b32 v214, v10, v11 offset0:68 offset1:102
	s_waitcnt lgkmcnt(0)
	s_barrier
	s_andn2_b64 vcc, exec, s[44:45]
	s_cbranch_vccnz .LBB0_417
	s_cmp_gt_u32 s84, s57
	s_cselect_b32 s4, s79, 0
	s_lshl_b32 s4, s4, 6
	s_sub_i32 s4, 0xc0, s4
	v_add_u32_e32 v10, s4, v221
	v_add_u32_e32 v11, s4, v222
	v_min_u32_e32 v10, 0x80ff, v10
	v_add_u32_e32 v13, 1, v11
	v_min_u32_e32 v11, 0x80ff, v11
	v_min_u32_e32 v13, 0x80ff, v13
	v_lshl_add_u32 v12, v10, 12, v238
	v_lshl_add_u32 v10, v10, 6, v239
	v_lshl_add_u32 v11, v11, 12, v174
	v_lshl_add_u32 v13, v13, 12, v174
	global_load_dwordx4 v[120:123], v12, s[98:99]
	global_load_dwordx4 v[124:127], v10, s[100:101]
	global_load_dwordx2 v[184:185], v11, s[98:99] offset:128
	global_load_dwordx2 v[186:187], v13, s[98:99] offset:128
	s_add_i32 s4, s83, 64
	v_cmp_le_u32_e32 vcc, s4, v220
	s_and_saveexec_b64 s[44:45], vcc
	s_cbranch_execz .LBB0_437
	v_add_u32_e32 v64, v202, v199
	ds_read_b128 v[10:13], v64
	ds_read_b128 v[136:139], v64 offset:32
	ds_read_b128 v[140:143], v64 offset:6656
	ds_read_b128 v[144:147], v64 offset:6688
	ds_read_b128 v[148:151], v64 offset:64
	ds_read_b128 v[152:155], v64 offset:96
	ds_read_b128 v[156:159], v64 offset:6720
	ds_read_b128 v[160:163], v64 offset:6752
	ds_read_b128 v[222:225], v64 offset:128
	ds_read_b128 v[226:229], v64 offset:160
	ds_read_b128 v[230:233], v64 offset:6784
	ds_read_b128 v[234:237], v64 offset:6816
	s_waitcnt lgkmcnt(11)
	v_mfma_f32_32x32x16_bf16 v[80:95], v[10:13], v[96:99], v[48:63]
	v_add_u32_e32 v10, v203, v164
	v_add_u32_e32 v11, 0x6800, v10
	v_add_u32_e32 v10, 0x7800, v10
	s_add_i32 s4, s83, 0x7f
	v_cmp_gt_i32_e32 vcc, s4, v175
	s_waitcnt lgkmcnt(9)
	v_mfma_f32_32x32x16_bf16 v[64:79], v[140:143], v[96:99], v[48:63]
	v_mfma_f32_32x32x16_bf16 v[80:95], v[136:139], v[100:103], v[80:95]
	s_waitcnt lgkmcnt(8)
	v_mfma_f32_32x32x16_bf16 v[64:79], v[144:147], v[100:103], v[64:79]
	s_waitcnt lgkmcnt(7)
	v_mfma_f32_32x32x16_bf16 v[80:95], v[148:151], v[104:107], v[80:95]
	s_waitcnt lgkmcnt(5)
	v_mfma_f32_32x32x16_bf16 v[64:79], v[156:159], v[104:107], v[64:79]
	v_mfma_f32_32x32x16_bf16 v[80:95], v[152:155], v[108:111], v[80:95]
	ds_read2_b64 v[152:155], v11 offset0:4 offset1:6
	s_waitcnt lgkmcnt(5)
	v_mfma_f32_32x32x16_bf16 v[64:79], v[160:163], v[108:111], v[64:79]
	ds_read2_b64 v[160:163], v11 offset1:2
	ds_read2_b64 v[156:159], v10 offset0:32 offset1:34
	ds_read2_b64 v[148:151], v10 offset0:36 offset1:38
	ds_read2_b64 v[144:147], v11 offset0:8 offset1:10
	ds_read2_b64 v[140:143], v10 offset0:40 offset1:42
	ds_read2_b64 v[136:139], v11 offset0:12 offset1:14
	ds_read2_b64 v[10:13], v10 offset0:44 offset1:46
	s_waitcnt lgkmcnt(11)
	v_mfma_f32_32x32x16_bf16 v[80:95], v[222:225], v[112:115], v[80:95]
	s_waitcnt lgkmcnt(9)
	v_mfma_f32_32x32x16_bf16 v[64:79], v[230:233], v[112:115], v[64:79]
	v_mfma_f32_32x32x16_bf16 v[80:95], v[226:229], v[116:119], v[80:95]
	s_waitcnt lgkmcnt(8)
	v_mfma_f32_32x32x16_bf16 v[64:79], v[234:237], v[116:119], v[64:79]
	s_and_saveexec_b64 s[46:47], vcc
	s_cbranch_execz .LBB0_434
; __device__ __forceinline__ void sm_pv(f32x16& s0, f32x16& s1, f32x16& o0, f32x16& o1, float& m_run, float& l_run, f32x16& negm, LAS unsigned char* vb, bool domask, int kbase, int qm, int r32, int hi) {
;     ...
;     if (domask) {
;         const int kb0 = kbase + 4 * hi;
; #pragma unroll
;         for (int r = 0; r < 16; ++r) { const int kv = kb0 + (r & 3) + 8 * (r >> 2); if (kv > qm) s0[r] = -INFINITY; if (kv + 32 > qm) s1[r] = -INFINITY; }
	v_add_u32_e32 v221, s83, v201
	v_add_u32_e32 v223, 0x60, v221
	v_add_u32_e32 v222, 64, v221
	v_cmp_le_u32_e64 s[4:5], v223, v219
	v_cmp_le_u32_e32 vcc, v222, v219
	s_nop 4
	v_cndmask_b32_e64 v64, v244, v64, s[4:5]
	v_cmp_lt_u32_e64 s[4:5], v222, v219
	v_add_u32_e32 v222, 0x61, v221
	v_cmp_le_u32_e64 s[6:7], v222, v219
	v_add_u32_e32 v222, 0x42, v221
	s_nop 0
	v_cndmask_b32_e64 v65, v244, v65, s[6:7]
	v_cmp_le_u32_e64 s[6:7], v222, v219
	v_add_u32_e32 v222, 0x62, v221
	v_cmp_le_u32_e64 s[8:9], v222, v219
	v_add_u32_e32 v222, 0x43, v221
	s_nop 0
	v_cndmask_b32_e64 v66, v244, v66, s[8:9]
	v_cmp_le_u32_e64 s[8:9], v222, v219
	v_add_u32_e32 v222, 0x63, v221
	v_cmp_le_u32_e64 s[10:11], v222, v219
	v_add_u32_e32 v222, 0x48, v221
	s_nop 0
	v_cndmask_b32_e64 v67, v244, v67, s[10:11]
	v_cmp_le_u32_e64 s[10:11], v222, v219
	v_add_u32_e32 v222, 0x68, v221
	v_cmp_le_u32_e64 s[12:13], v222, v219
	v_add_u32_e32 v222, 0x49, v221
	s_nop 0
	v_cndmask_b32_e64 v68, v244, v68, s[12:13]
	v_cmp_le_u32_e64 s[12:13], v222, v219
	v_add_u32_e32 v222, 0x69, v221
	v_cmp_le_u32_e64 s[14:15], v222, v219
	v_add_u32_e32 v222, 0x4a, v221
	s_nop 0
	v_cndmask_b32_e64 v69, v244, v69, s[14:15]
	v_cmp_le_u32_e64 s[14:15], v222, v219
	v_add_u32_e32 v222, 0x6a, v221
	v_cmp_le_u32_e64 s[16:17], v222, v219
	v_add_u32_e32 v222, 0x4b, v221
	s_nop 0
	v_cndmask_b32_e64 v70, v244, v70, s[16:17]
	v_cmp_le_u32_e64 s[16:17], v222, v219
	v_add_u32_e32 v222, 0x6b, v221
	v_cmp_le_u32_e64 s[18:19], v222, v219
	v_add_u32_e32 v222, 0x50, v221
	s_nop 0
	v_cndmask_b32_e64 v71, v244, v71, s[18:19]
	v_cmp_le_u32_e64 s[18:19], v222, v219
	v_add_u32_e32 v222, 0x70, v221
	v_cmp_le_u32_e64 s[20:21], v222, v219
	v_add_u32_e32 v222, 0x51, v221
	s_nop 0
	v_cndmask_b32_e64 v72, v244, v72, s[20:21]
	v_cmp_le_u32_e64 s[20:21], v222, v219
	v_add_u32_e32 v222, 0x71, v221
	v_cmp_le_u32_e64 s[22:23], v222, v219
	v_add_u32_e32 v222, 0x52, v221
	s_nop 0
	v_cndmask_b32_e64 v73, v244, v73, s[22:23]
	v_cmp_le_u32_e64 s[22:23], v222, v219
	v_add_u32_e32 v222, 0x72, v221
	v_cmp_le_u32_e64 s[24:25], v222, v219
	v_add_u32_e32 v222, 0x53, v221
	s_nop 0
	v_cndmask_b32_e64 v74, v244, v74, s[24:25]
	v_cmp_le_u32_e64 s[24:25], v222, v219
	v_add_u32_e32 v222, 0x73, v221
	v_cmp_le_u32_e64 s[26:27], v222, v219
	v_add_u32_e32 v222, 0x58, v221
	s_nop 0
	v_cndmask_b32_e64 v75, v244, v75, s[26:27]
	v_cmp_le_u32_e64 s[26:27], v222, v219
	v_add_u32_e32 v222, 0x78, v221
	v_cmp_le_u32_e64 s[28:29], v222, v219
	v_add_u32_e32 v222, 0x59, v221
	s_nop 0
	v_cndmask_b32_e64 v76, v244, v76, s[28:29]
	v_cmp_le_u32_e64 s[28:29], v222, v219
	v_add_u32_e32 v222, 0x79, v221
	v_cmp_le_u32_e64 s[30:31], v222, v219
	v_add_u32_e32 v222, 0x5a, v221
	s_nop 0
	v_cndmask_b32_e64 v77, v244, v77, s[30:31]
	v_cmp_le_u32_e64 s[30:31], v222, v219
	v_add_u32_e32 v222, 0x7a, v221
	v_cmp_le_u32_e64 s[34:35], v222, v219
	v_add_u32_e32 v222, 0x5b, v221
	v_add_u32_e32 v221, 0x7b, v221
	v_cndmask_b32_e64 v78, v244, v78, s[34:35]
	v_cmp_le_u32_e64 s[34:35], v222, v219
	v_cmp_gt_u32_e64 s[36:37], v221, v219
	s_and_saveexec_b64 s[40:41], s[36:37]
	v_mov_b32_e32 v79, s52
	s_or_b64 exec, exec, s[40:41]
	v_cndmask_b32_e64 v81, v244, v81, s[4:5]
	v_cndmask_b32_e32 v80, v244, v80, vcc
	v_cndmask_b32_e64 v82, v244, v82, s[6:7]
	v_cndmask_b32_e64 v83, v244, v83, s[8:9]
	v_cndmask_b32_e64 v84, v244, v84, s[10:11]
	v_cndmask_b32_e64 v85, v244, v85, s[12:13]
	v_cndmask_b32_e64 v86, v244, v86, s[14:15]
	v_cndmask_b32_e64 v87, v244, v87, s[16:17]
	v_cndmask_b32_e64 v88, v244, v88, s[18:19]
	v_cndmask_b32_e64 v89, v244, v89, s[20:21]
	v_cndmask_b32_e64 v90, v244, v90, s[22:23]
	v_cndmask_b32_e64 v91, v244, v91, s[24:25]
	v_cndmask_b32_e64 v92, v244, v92, s[26:27]
	v_cndmask_b32_e64 v93, v244, v93, s[28:29]
	v_cndmask_b32_e64 v94, v244, v94, s[30:31]
	v_cndmask_b32_e64 v95, v244, v95, s[34:35]

; #define LAS __attribute__((address_space(3)))
; __device__ __forceinline__ void qk_tile(f32x16& s0, f32x16& s1, LAS unsigned char* kb, const bf16x8 (&qr)[6], const f32x16& negm, int r32, int hi) {
;     bf16x8 kf[12];
; #pragma unroll
;     for (int ks = 0; ks < 6; ++ks) { kf[2 * ks] = *(const LAS bf16x8*)(kb + r32 * KPT + ks * 32 + hi * 16); kf[2 * ks + 1] = *(const LAS bf16x8*)(kb + (32 + r32) * KPT + ks * 32 + hi * 16); }
;     __builtin_amdgcn_sched_barrier(0);
; #pragma unroll
;     for (int ks = 0; ks < 6; ++ks) {
;         s0 = __builtin_amdgcn_mfma_f32_32x32x16_bf16(kf[2 * ks], qr[ks], ks == 0 ? negm : s0, 0, 0, 0);
;         s1 = __builtin_amdgcn_mfma_f32_32x32x16_bf16(kf[2 * ks + 1], qr[ks], ks == 0 ? negm : s1, 0, 0, 0);
;     }
; }
; __device__ __forceinline__ void sm_pv(f32x16& s0, f32x16& s1, f32x16& o0, f32x16& o1, float& m_run, float& l_run, f32x16& negm, LAS unsigned char* vb, bool domask, int kbase, int qm, int r32, int hi) {
;     s16x4 vlo[8], vhh[8];
; #pragma unroll
;     for (int kk = 0; kk < 4; ++kk) { const int koff = 2 * (16 * kk + 4 * hi);
;         vlo[2 * kk] = *(const LAS s16x4*)(vb + r32 * VP + koff); vhh[2 * kk] = *(const LAS s16x4*)(vb + r32 * VP + koff + 16);
;         vlo[2 * kk + 1] = *(const LAS s16x4*)(vb + (32 + r32) * VP + koff); vhh[2 * kk + 1] = *(const LAS s16x4*)(vb + (32 + r32) * VP + koff + 16); }
;     __builtin_amdgcn_sched_barrier(0);
;     if (domask) {
;         const int kb0 = kbase + 4 * hi;
; #pragma unroll
;         for (int r = 0; r < 16; ++r) { const int kv = kb0 + (r & 3) + 8 * (r >> 2); if (kv > qm) s0[r] = -INFINITY; if (kv + 32 > qm) s1[r] = -INFINITY; }
.LBB0_443:
	s_add_i32 s85, s84, -3
	s_cmp_lt_u32 s85, s57
	s_cselect_b64 s[44:45], -1, 0
	s_and_b64 s[4:5], s[44:45], exec
	s_cselect_b32 s4, 0, s79
	s_lshl_b32 s4, s4, 6
	s_sub_i32 s5, 0x80, s4
	v_add_u32_e32 v14, s83, v213
	v_add_u32_e32 v15, s83, v173
	v_add_u32_e32 v2, s5, v14
	v_add_u32_e32 v3, s5, v15
	v_min_u32_e32 v2, 0x80ff, v2
	v_add_u32_e32 v5, 1, v3
	v_min_u32_e32 v3, 0x80ff, v3
	v_min_u32_e32 v5, 0x80ff, v5
	v_lshl_add_u32 v4, v2, 12, v238
	v_lshl_add_u32 v2, v2, 6, v239
	v_lshl_add_u32 v3, v3, 12, v174
	v_lshl_add_u32 v5, v5, 12, v174
	global_load_dwordx4 v[120:123], v4, s[98:99]
	global_load_dwordx4 v[124:127], v2, s[100:101]
	global_load_dwordx2 v[184:185], v3, s[98:99] offset:128
	global_load_dwordx2 v[186:187], v5, s[98:99] offset:128
	v_cmp_le_u32_e32 vcc, s83, v220
	s_and_saveexec_b64 s[46:47], vcc
	s_cbranch_execz .LBB0_451
	v_add_u32_e32 v64, v202, v199
	ds_read_b128 v[2:5], v64
	ds_read_b128 v[6:9], v64 offset:32
	ds_read_b128 v[10:13], v64 offset:6656
	ds_read_b128 v[136:139], v64 offset:6688
	ds_read_b128 v[140:143], v64 offset:64
	ds_read_b128 v[144:147], v64 offset:96
	ds_read_b128 v[148:151], v64 offset:6720
	ds_read_b128 v[152:155], v64 offset:6752
	ds_read_b128 v[156:159], v64 offset:128
	ds_read_b128 v[160:163], v64 offset:160
	ds_read_b128 v[222:225], v64 offset:6784
	ds_read_b128 v[226:229], v64 offset:6816
	s_waitcnt lgkmcnt(11)
	v_mfma_f32_32x32x16_bf16 v[80:95], v[2:5], v[96:99], v[48:63]
	v_add_u32_e32 v2, v203, v164
	v_add_u32_e32 v3, 0x6800, v2
	v_add_u32_e32 v2, 0x7800, v2
	s_add_i32 s4, s83, 63
	v_cmp_gt_i32_e32 vcc, s4, v175
	s_waitcnt lgkmcnt(9)
	v_mfma_f32_32x32x16_bf16 v[64:79], v[10:13], v[96:99], v[48:63]
	v_mfma_f32_32x32x16_bf16 v[80:95], v[6:9], v[100:103], v[80:95]
	s_waitcnt lgkmcnt(8)
	v_mfma_f32_32x32x16_bf16 v[64:79], v[136:139], v[100:103], v[64:79]
	s_waitcnt lgkmcnt(7)
	v_mfma_f32_32x32x16_bf16 v[80:95], v[140:143], v[104:107], v[80:95]
	s_waitcnt lgkmcnt(5)
	v_mfma_f32_32x32x16_bf16 v[64:79], v[148:151], v[104:107], v[64:79]
	v_mfma_f32_32x32x16_bf16 v[80:95], v[144:147], v[108:111], v[80:95]
	ds_read2_b64 v[144:147], v3 offset0:4 offset1:6
	s_waitcnt lgkmcnt(5)
	v_mfma_f32_32x32x16_bf16 v[64:79], v[152:155], v[108:111], v[64:79]
	ds_read2_b64 v[152:155], v3 offset1:2
	ds_read2_b64 v[148:151], v2 offset0:32 offset1:34
	ds_read2_b64 v[140:143], v2 offset0:36 offset1:38
	ds_read2_b64 v[136:139], v3 offset0:8 offset1:10
	ds_read2_b64 v[10:13], v2 offset0:40 offset1:42
	ds_read2_b64 v[6:9], v3 offset0:12 offset1:14
	ds_read2_b64 v[2:5], v2 offset0:44 offset1:46
	s_waitcnt lgkmcnt(11)
	v_mfma_f32_32x32x16_bf16 v[80:95], v[156:159], v[112:115], v[80:95]
	s_waitcnt lgkmcnt(9)
	v_mfma_f32_32x32x16_bf16 v[64:79], v[222:225], v[112:115], v[64:79]
	v_mfma_f32_32x32x16_bf16 v[80:95], v[160:163], v[116:119], v[80:95]
	s_waitcnt lgkmcnt(8)
	v_mfma_f32_32x32x16_bf16 v[64:79], v[226:229], v[116:119], v[64:79]
	s_and_saveexec_b64 s[58:59], vcc
	s_cbranch_execz .LBB0_448
	v_add_u32_e32 v156, s83, v201
	v_add_u32_e32 v157, 32, v156
	v_cmp_ge_i32_e64 s[4:5], v177, v157
	v_add_u32_e32 v157, 33, v156
	v_cmp_ge_i32_e64 s[6:7], v177, v157
	v_add_u32_e32 v157, 2, v156
	v_cmp_le_u32_e32 vcc, v156, v219
	s_nop 2
	v_cndmask_b32_e64 v65, v244, v65, s[6:7]
	v_cmp_ge_i32_e64 s[6:7], v177, v157
	v_add_u32_e32 v157, 34, v156
	v_cmp_ge_i32_e64 s[8:9], v177, v157
	v_add_u32_e32 v157, 3, v156
	v_cndmask_b32_e64 v64, v244, v64, s[4:5]
	v_cndmask_b32_e64 v66, v244, v66, s[8:9]
	v_cmp_ge_i32_e64 s[8:9], v177, v157
	v_add_u32_e32 v157, 35, v156
	v_cmp_ge_i32_e64 s[10:11], v177, v157
	v_add_u32_e32 v157, 8, v156
	v_cmp_gt_i32_e64 s[4:5], v177, v156
	v_cndmask_b32_e64 v67, v244, v67, s[10:11]
	v_cmp_ge_i32_e64 s[10:11], v177, v157
	v_add_u32_e32 v157, 40, v156
	v_cmp_ge_i32_e64 s[12:13], v177, v157
	v_add_u32_e32 v157, 9, v156
	s_nop 0
	v_cndmask_b32_e64 v68, v244, v68, s[12:13]
	v_cmp_ge_i32_e64 s[12:13], v177, v157
	v_add_u32_e32 v157, 41, v156
	v_cmp_ge_i32_e64 s[14:15], v177, v157
	v_add_u32_e32 v157, 10, v156
	s_nop 0
	v_cndmask_b32_e64 v69, v244, v69, s[14:15]
	v_cmp_ge_i32_e64 s[14:15], v177, v157
	v_add_u32_e32 v157, 42, v156
	v_cmp_ge_i32_e64 s[16:17], v177, v157
	v_add_u32_e32 v157, 11, v156
	s_nop 0
	v_cndmask_b32_e64 v70, v244, v70, s[16:17]
	v_cmp_ge_i32_e64 s[16:17], v177, v157
	v_add_u32_e32 v157, 43, v156
	v_cmp_ge_i32_e64 s[18:19], v177, v157
	v_add_u32_e32 v157, 16, v156
	s_nop 0
	v_cndmask_b32_e64 v71, v244, v71, s[18:19]
	v_cmp_ge_i32_e64 s[18:19], v177, v157
	v_add_u32_e32 v157, 48, v156
	v_cmp_ge_i32_e64 s[20:21], v177, v157
	v_add_u32_e32 v157, 17, v156
	s_nop 0
	v_cndmask_b32_e64 v72, v244, v72, s[20:21]
	v_cmp_ge_i32_e64 s[20:21], v177, v157
	v_add_u32_e32 v157, 49, v156
	v_cmp_ge_i32_e64 s[22:23], v177, v157
	v_add_u32_e32 v157, 18, v156
	s_nop 0
	v_cndmask_b32_e64 v73, v244, v73, s[22:23]
	v_cmp_ge_i32_e64 s[22:23], v177, v157
	v_add_u32_e32 v157, 50, v156
	v_cmp_ge_i32_e64 s[24:25], v177, v157
	v_add_u32_e32 v157, 19, v156
	s_nop 0
	v_cndmask_b32_e64 v74, v244, v74, s[24:25]
	v_cmp_ge_i32_e64 s[24:25], v177, v157
	v_add_u32_e32 v157, 51, v156
	v_cmp_ge_i32_e64 s[26:27], v177, v157
	v_add_u32_e32 v157, 24, v156
	s_nop 0
	v_cndmask_b32_e64 v75, v244, v75, s[26:27]
	v_cmp_ge_i32_e64 s[26:27], v177, v157
	v_add_u32_e32 v157, 56, v156
	v_cmp_ge_i32_e64 s[28:29], v177, v157
	v_add_u32_e32 v157, 25, v156
	s_nop 0
	v_cndmask_b32_e64 v76, v244, v76, s[28:29]
	v_cmp_ge_i32_e64 s[28:29], v177, v157
	v_add_u32_e32 v157, 57, v156
	v_cmp_ge_i32_e64 s[30:31], v177, v157
	v_add_u32_e32 v157, 26, v156
	s_nop 0
	v_cndmask_b32_e64 v77, v244, v77, s[30:31]
	v_cmp_ge_i32_e64 s[30:31], v177, v157
	v_add_u32_e32 v157, 58, v156
	v_cmp_ge_i32_e64 s[34:35], v177, v157
	v_add_u32_e32 v157, 27, v156
	v_add_u32_e32 v156, 59, v156
	v_cndmask_b32_e64 v78, v244, v78, s[34:35]
	v_cmp_ge_i32_e64 s[34:35], v177, v157
	v_cmp_lt_i32_e64 s[36:37], v177, v156
	s_and_saveexec_b64 s[40:41], s[36:37]
	v_mov_b32_e32 v79, s52
	s_or_b64 exec, exec, s[40:41]
	v_cndmask_b32_e32 v80, v244, v80, vcc
	v_cndmask_b32_e64 v81, v244, v81, s[4:5]
	v_cndmask_b32_e64 v82, v244, v82, s[6:7]
	v_cndmask_b32_e64 v83, v244, v83, s[8:9]
	v_cndmask_b32_e64 v84, v244, v84, s[10:11]
	v_cndmask_b32_e64 v85, v244, v85, s[12:13]
	v_cndmask_b32_e64 v86, v244, v86, s[14:15]
	v_cndmask_b32_e64 v87, v244, v87, s[16:17]
	v_cndmask_b32_e64 v88, v244, v88, s[18:19]
	v_cndmask_b32_e64 v89, v244, v89, s[20:21]
	v_cndmask_b32_e64 v90, v244, v90, s[22:23]
	v_cndmask_b32_e64 v91, v244, v91, s[24:25]
	v_cndmask_b32_e64 v92, v244, v92, s[26:27]
	v_cndmask_b32_e64 v93, v244, v93, s[28:29]
	v_cndmask_b32_e64 v94, v244, v94, s[30:31]
	v_cndmask_b32_e64 v95, v244, v95, s[34:35]

; #define LAS __attribute__((address_space(3)))
; __device__ __forceinline__ void qk_tile(f32x16& s0, f32x16& s1, LAS unsigned char* kb, const bf16x8 (&qr)[6], const f32x16& negm, int r32, int hi) {
;     bf16x8 kf[12];
; #pragma unroll
;     for (int ks = 0; ks < 6; ++ks) { kf[2 * ks] = *(const LAS bf16x8*)(kb + r32 * KPT + ks * 32 + hi * 16); kf[2 * ks + 1] = *(const LAS bf16x8*)(kb + (32 + r32) * KPT + ks * 32 + hi * 16); }
;     __builtin_amdgcn_sched_barrier(0);
; #pragma unroll
;     for (int ks = 0; ks < 6; ++ks) {
;         s0 = __builtin_amdgcn_mfma_f32_32x32x16_bf16(kf[2 * ks], qr[ks], ks == 0 ? negm : s0, 0, 0, 0);
;         s1 = __builtin_amdgcn_mfma_f32_32x32x16_bf16(kf[2 * ks + 1], qr[ks], ks == 0 ? negm : s1, 0, 0, 0);
;     }
.LBB0_453:
	s_or_b64 exec, exec, s[4:5]
	s_waitcnt vmcnt(5)
	v_and_b32_e32 v2, 0xffff, v188
	v_lshrrev_b32_e32 v3, 16, v188
	s_waitcnt vmcnt(4)
	v_lshl_or_b32 v2, v190, 16, v2
	v_and_or_b32 v3, v190, s81, v3
	v_add_u32_e32 v4, 0x8800, v211
	ds_write2_b32 v4, v2, v3 offset0:128 offset1:162
	v_and_b32_e32 v2, 0xffff, v189
	v_lshrrev_b32_e32 v3, 16, v189
	v_lshl_or_b32 v2, v191, 16, v2
	v_and_or_b32 v3, v191, s81, v3
	ds_write2_b32 v4, v2, v3 offset0:196 offset1:230
	s_waitcnt lgkmcnt(0)
	s_barrier
	s_andn2_b64 vcc, exec, s[44:45]
	s_cbranch_vccnz .LBB0_442
	s_cmp_gt_u32 s84, s57
	s_cselect_b32 s4, s79, 0
	s_lshl_b32 s4, s4, 6
	s_sub_i32 s4, 0xc0, s4
	v_add_u32_e32 v2, s4, v14
	v_add_u32_e32 v3, s4, v15
	v_min_u32_e32 v2, 0x80ff, v2
	v_add_u32_e32 v5, 1, v3
	v_min_u32_e32 v3, 0x80ff, v3
	v_min_u32_e32 v5, 0x80ff, v5
	v_lshl_add_u32 v4, v2, 12, v238
	v_lshl_add_u32 v2, v2, 6, v239
	v_lshl_add_u32 v3, v3, 12, v174
	v_lshl_add_u32 v5, v5, 12, v174
	global_load_dwordx4 v[128:131], v4, s[98:99]
	global_load_dwordx4 v[132:135], v2, s[100:101]
	global_load_dwordx2 v[188:189], v3, s[98:99] offset:128
	global_load_dwordx2 v[190:191], v5, s[98:99] offset:128
	s_add_i32 s4, s83, 64
	v_cmp_le_u32_e32 vcc, s4, v220
	s_and_saveexec_b64 s[44:45], vcc
	s_cbranch_execz .LBB0_462
	v_add_u32_e32 v14, v198, v199
	ds_read_b128 v[2:5], v14 offset:13312
	ds_read_b128 v[6:9], v14 offset:13344
	ds_read_b128 v[10:13], v14 offset:19968
	ds_read_b128 v[136:139], v14 offset:20000
	ds_read_b128 v[140:143], v14 offset:13376
	ds_read_b128 v[144:147], v14 offset:13408
	ds_read_b128 v[148:151], v14 offset:20032
	ds_read_b128 v[152:155], v14 offset:20064
	ds_read_b128 v[156:159], v14 offset:13440
	ds_read_b128 v[160:163], v14 offset:13472
	ds_read_b128 v[222:225], v14 offset:20096
	ds_read_b128 v[226:229], v14 offset:20128
	s_waitcnt lgkmcnt(11)
	v_mfma_f32_32x32x16_bf16 v[80:95], v[2:5], v[96:99], v[48:63]
	v_add_u32_e32 v2, v200, v164
	v_add_u32_e32 v3, 0x8800, v2
	v_add_u32_e32 v2, 0x9800, v2
	s_add_i32 s4, s83, 0x7f
	v_cmp_gt_i32_e32 vcc, s4, v175
	s_waitcnt lgkmcnt(9)
	v_mfma_f32_32x32x16_bf16 v[64:79], v[10:13], v[96:99], v[48:63]
	v_mfma_f32_32x32x16_bf16 v[80:95], v[6:9], v[100:103], v[80:95]
	s_waitcnt lgkmcnt(8)
	v_mfma_f32_32x32x16_bf16 v[64:79], v[136:139], v[100:103], v[64:79]
	s_waitcnt lgkmcnt(7)
	v_mfma_f32_32x32x16_bf16 v[80:95], v[140:143], v[104:107], v[80:95]
	s_waitcnt lgkmcnt(5)
	v_mfma_f32_32x32x16_bf16 v[64:79], v[148:151], v[104:107], v[64:79]
	v_mfma_f32_32x32x16_bf16 v[80:95], v[144:147], v[108:111], v[80:95]
	ds_read2_b64 v[144:147], v3 offset0:68 offset1:70
	s_waitcnt lgkmcnt(5)
	v_mfma_f32_32x32x16_bf16 v[64:79], v[152:155], v[108:111], v[64:79]
	ds_read2_b64 v[152:155], v3 offset0:64 offset1:66
	ds_read2_b64 v[148:151], v2 offset0:96 offset1:98
	ds_read2_b64 v[140:143], v2 offset0:100 offset1:102
	ds_read2_b64 v[136:139], v3 offset0:72 offset1:74
	ds_read2_b64 v[10:13], v2 offset0:104 offset1:106
	ds_read2_b64 v[6:9], v3 offset0:76 offset1:78
	ds_read2_b64 v[2:5], v2 offset0:108 offset1:110
	s_waitcnt lgkmcnt(11)
	v_mfma_f32_32x32x16_bf16 v[80:95], v[156:159], v[112:115], v[80:95]
	s_waitcnt lgkmcnt(9)
	v_mfma_f32_32x32x16_bf16 v[64:79], v[222:225], v[112:115], v[64:79]
	v_mfma_f32_32x32x16_bf16 v[80:95], v[160:163], v[116:119], v[80:95]
	s_waitcnt lgkmcnt(8)
	v_mfma_f32_32x32x16_bf16 v[64:79], v[226:229], v[116:119], v[64:79]
	s_and_saveexec_b64 s[46:47], vcc
	s_cbranch_execz .LBB0_459
; __device__ __forceinline__ void sm_pv(f32x16& s0, f32x16& s1, f32x16& o0, f32x16& o1, float& m_run, float& l_run, f32x16& negm, LAS unsigned char* vb, bool domask, int kbase, int qm, int r32, int hi) {
;     ...
;     if (domask) {
;         const int kb0 = kbase + 4 * hi;
; #pragma unroll
;         for (int r = 0; r < 16; ++r) { const int kv = kb0 + (r & 3) + 8 * (r >> 2); if (kv > qm) s0[r] = -INFINITY; if (kv + 32 > qm) s1[r] = -INFINITY; }
	v_add_u32_e32 v14, s83, v201
	v_add_u32_e32 v156, 0x60, v14
	v_add_u32_e32 v15, 64, v14
	v_cmp_le_u32_e64 s[4:5], v156, v219
	v_cmp_le_u32_e32 vcc, v15, v219
	s_nop 4
	v_cndmask_b32_e64 v64, v244, v64, s[4:5]
	v_cmp_lt_u32_e64 s[4:5], v15, v219
	v_add_u32_e32 v15, 0x61, v14
	v_cmp_le_u32_e64 s[6:7], v15, v219
	v_add_u32_e32 v15, 0x42, v14
	s_nop 0
	v_cndmask_b32_e64 v65, v244, v65, s[6:7]
	v_cmp_le_u32_e64 s[6:7], v15, v219
	v_add_u32_e32 v15, 0x62, v14
	v_cmp_le_u32_e64 s[8:9], v15, v219
	v_add_u32_e32 v15, 0x43, v14
	s_nop 0
	v_cndmask_b32_e64 v66, v244, v66, s[8:9]
	v_cmp_le_u32_e64 s[8:9], v15, v219
	v_add_u32_e32 v15, 0x63, v14
	v_cmp_le_u32_e64 s[10:11], v15, v219
	v_add_u32_e32 v15, 0x48, v14
	s_nop 0
	v_cndmask_b32_e64 v67, v244, v67, s[10:11]
	v_cmp_le_u32_e64 s[10:11], v15, v219
	v_add_u32_e32 v15, 0x68, v14
	v_cmp_le_u32_e64 s[12:13], v15, v219
	v_add_u32_e32 v15, 0x49, v14
	s_nop 0
	v_cndmask_b32_e64 v68, v244, v68, s[12:13]
	v_cmp_le_u32_e64 s[12:13], v15, v219
	v_add_u32_e32 v15, 0x69, v14
	v_cmp_le_u32_e64 s[14:15], v15, v219
	v_add_u32_e32 v15, 0x4a, v14
	s_nop 0
	v_cndmask_b32_e64 v69, v244, v69, s[14:15]
	v_cmp_le_u32_e64 s[14:15], v15, v219
	v_add_u32_e32 v15, 0x6a, v14
	v_cmp_le_u32_e64 s[16:17], v15, v219
	v_add_u32_e32 v15, 0x4b, v14
	s_nop 0
	v_cndmask_b32_e64 v70, v244, v70, s[16:17]
	v_cmp_le_u32_e64 s[16:17], v15, v219
	v_add_u32_e32 v15, 0x6b, v14
	v_cmp_le_u32_e64 s[18:19], v15, v219
	v_add_u32_e32 v15, 0x50, v14
	s_nop 0
	v_cndmask_b32_e64 v71, v244, v71, s[18:19]
	v_cmp_le_u32_e64 s[18:19], v15, v219
	v_add_u32_e32 v15, 0x70, v14
	v_cmp_le_u32_e64 s[20:21], v15, v219
	v_add_u32_e32 v15, 0x51, v14
	s_nop 0
	v_cndmask_b32_e64 v72, v244, v72, s[20:21]
	v_cmp_le_u32_e64 s[20:21], v15, v219
	v_add_u32_e32 v15, 0x71, v14
	v_cmp_le_u32_e64 s[22:23], v15, v219
	v_add_u32_e32 v15, 0x52, v14
	s_nop 0
	v_cndmask_b32_e64 v73, v244, v73, s[22:23]
	v_cmp_le_u32_e64 s[22:23], v15, v219
	v_add_u32_e32 v15, 0x72, v14
	v_cmp_le_u32_e64 s[24:25], v15, v219
	v_add_u32_e32 v15, 0x53, v14
	s_nop 0
	v_cndmask_b32_e64 v74, v244, v74, s[24:25]
	v_cmp_le_u32_e64 s[24:25], v15, v219
	v_add_u32_e32 v15, 0x73, v14
	v_cmp_le_u32_e64 s[26:27], v15, v219
	v_add_u32_e32 v15, 0x58, v14
	s_nop 0
	v_cndmask_b32_e64 v75, v244, v75, s[26:27]
	v_cmp_le_u32_e64 s[26:27], v15, v219
	v_add_u32_e32 v15, 0x78, v14
	v_cmp_le_u32_e64 s[28:29], v15, v219
	v_add_u32_e32 v15, 0x59, v14
	s_nop 0
	v_cndmask_b32_e64 v76, v244, v76, s[28:29]
	v_cmp_le_u32_e64 s[28:29], v15, v219
	v_add_u32_e32 v15, 0x79, v14
	v_cmp_le_u32_e64 s[30:31], v15, v219
	v_add_u32_e32 v15, 0x5a, v14
	s_nop 0
	v_cndmask_b32_e64 v77, v244, v77, s[30:31]
	v_cmp_le_u32_e64 s[30:31], v15, v219
	v_add_u32_e32 v15, 0x7a, v14
	v_cmp_le_u32_e64 s[34:35], v15, v219
	v_add_u32_e32 v15, 0x5b, v14
	v_add_u32_e32 v14, 0x7b, v14
	v_cndmask_b32_e64 v78, v244, v78, s[34:35]
	v_cmp_le_u32_e64 s[34:35], v15, v219
	v_cmp_gt_u32_e64 s[36:37], v14, v219
	s_and_saveexec_b64 s[40:41], s[36:37]
	v_mov_b32_e32 v79, s52
	s_or_b64 exec, exec, s[40:41]
	v_cndmask_b32_e64 v81, v244, v81, s[4:5]
	v_cndmask_b32_e32 v80, v244, v80, vcc
	v_cndmask_b32_e64 v82, v244, v82, s[6:7]
	v_cndmask_b32_e64 v83, v244, v83, s[8:9]
	v_cndmask_b32_e64 v84, v244, v84, s[10:11]
	v_cndmask_b32_e64 v85, v244, v85, s[12:13]
	v_cndmask_b32_e64 v86, v244, v86, s[14:15]
	v_cndmask_b32_e64 v87, v244, v87, s[16:17]
	v_cndmask_b32_e64 v88, v244, v88, s[18:19]
	v_cndmask_b32_e64 v89, v244, v89, s[20:21]
	v_cndmask_b32_e64 v90, v244, v90, s[22:23]
	v_cndmask_b32_e64 v91, v244, v91, s[24:25]
	v_cndmask_b32_e64 v92, v244, v92, s[26:27]
	v_cndmask_b32_e64 v93, v244, v93, s[28:29]
	v_cndmask_b32_e64 v94, v244, v94, s[30:31]
	v_cndmask_b32_e64 v95, v244, v95, s[34:35]

; __global__ void __launch_bounds__(512, 2) hybrid_fwd(Params p_unused) {
	.amdhsa_kernel _Z10hybrid_fwd6Params
		.amdhsa_group_segment_fixed_size 0
		.amdhsa_private_segment_fixed_size 0
		.amdhsa_kernarg_size 480
		.amdhsa_user_sgpr_count 2
		.amdhsa_user_sgpr_dispatch_ptr 0
		.amdhsa_user_sgpr_queue_ptr 0
		.amdhsa_user_sgpr_kernarg_segment_ptr 1
		.amdhsa_user_sgpr_dispatch_id 0
		.amdhsa_user_sgpr_kernarg_preload_length 0
		.amdhsa_user_sgpr_kernarg_preload_offset 0
		.amdhsa_user_sgpr_private_segment_size 0
		.amdhsa_uses_dynamic_stack 0
		.amdhsa_enable_private_segment 0
		.amdhsa_system_sgpr_workgroup_id_x 1
		.amdhsa_system_sgpr_workgroup_id_y 0
		.amdhsa_system_sgpr_workgroup_id_z 0
		.amdhsa_system_sgpr_workgroup_info 0
		.amdhsa_system_vgpr_workitem_id 2
		.amdhsa_next_free_vgpr 256
		.amdhsa_next_free_sgpr 102
		.amdhsa_accum_offset 256
		.amdhsa_reserve_vcc 1
		.amdhsa_float_round_mode_32 0
		.amdhsa_float_round_mode_16_64 0
		.amdhsa_float_denorm_mode_32 3
		.amdhsa_float_denorm_mode_16_64 3
		.amdhsa_dx10_clamp 1
		.amdhsa_ieee_mode 1
		.amdhsa_fp16_overflow 0
		.amdhsa_tg_split 0
		.amdhsa_exception_fp_ieee_invalid_op 0
		.amdhsa_exception_fp_denorm_src 0
		.amdhsa_exception_fp_ieee_div_zero 0
		.amdhsa_exception_fp_ieee_overflow 0
		.amdhsa_exception_fp_ieee_underflow 0
		.amdhsa_exception_fp_ieee_inexact 0
		.amdhsa_exception_int_div_zero 0
	.end_amdhsa_kernel

; __global__ void __launch_bounds__(512, 2) hybrid_fwd(Params p_unused) {
.Lfunc_end0:
	.size	_Z10hybrid_fwd6Params, .Lfunc_end0-_Z10hybrid_fwd6Params
	.set _Z10hybrid_fwd6Params.num_vgpr, 256
	.set _Z10hybrid_fwd6Params.num_agpr, 0
	.set _Z10hybrid_fwd6Params.numbered_sgpr, 102
	.set _Z10hybrid_fwd6Params.num_named_barrier, 0
	.set _Z10hybrid_fwd6Params.private_seg_size, 0
	.set _Z10hybrid_fwd6Params.uses_vcc, 1
	.set _Z10hybrid_fwd6Params.uses_flat_scratch, 0
	.set _Z10hybrid_fwd6Params.has_dyn_sized_stack, 0
	.set _Z10hybrid_fwd6Params.has_recursion, 0
	.set _Z10hybrid_fwd6Params.has_indirect_call, 0

; __global__ void __launch_bounds__(512, 2) hybrid_fwd(Params p_unused) {
amdhsa.kernels:
  - .agpr_count:     0
    .args:
      - .offset:         0
        .size:           224
        .value_kind:     by_value
      - .offset:         224
        .size:           4
        .value_kind:     hidden_block_count_x
      - .offset:         228
        .size:           4
        .value_kind:     hidden_block_count_y
      - .offset:         232
        .size:           4
        .value_kind:     hidden_block_count_z
      - .offset:         236
        .size:           2
        .value_kind:     hidden_group_size_x
      - .offset:         238
        .size:           2
        .value_kind:     hidden_group_size_y
      - .offset:         240
        .size:           2
        .value_kind:     hidden_group_size_z
      - .offset:         242
        .size:           2
        .value_kind:     hidden_remainder_x
      - .offset:         244
        .size:           2
        .value_kind:     hidden_remainder_y
      - .offset:         246
        .size:           2
        .value_kind:     hidden_remainder_z
      - .offset:         264
        .size:           8
        .value_kind:     hidden_global_offset_x
      - .offset:         272
        .size:           8
        .value_kind:     hidden_global_offset_y
      - .offset:         280
        .size:           8
        .value_kind:     hidden_global_offset_z
      - .offset:         288
        .size:           2
        .value_kind:     hidden_grid_dims
      - .offset:         312
        .size:           8
        .value_kind:     hidden_multigrid_sync_arg
      - .offset:         344
        .size:           4
        .value_kind:     hidden_dynamic_lds_size
    .group_segment_fixed_size: 0
    .kernarg_segment_align: 8
    .kernarg_segment_size: 480
    .language:       OpenCL C
    .language_version:
      - 2
      - 0
    .max_flat_workgroup_size: 512
    .name:           _Z10hybrid_fwd6Params
    .private_segment_fixed_size: 0
    .sgpr_count:     108
    .sgpr_spill_count: 80
    .symbol:         _Z10hybrid_fwd6Params.kd
    .uniform_work_group_size: 1
    .uses_dynamic_stack: false
    .vgpr_count:     256
    .vgpr_spill_count: 0
    .wavefront_size: 64
